# GEMM4 fused-norm epilogue: the eight per-row-group ssq loads issued up front, per-group waits no longer cover the newest atomic
# baseline (speedup 1.0000x reference)
; DI float bflo(unsigned w) { return __uint_as_float(w << 16); }
; DI float bfhi(unsigned w) { return __uint_as_float(w & 0xffff0000u); }
; #define EF_LOAD(slot_, g_) do { const size_t o_ = (size_t)(row0 + ((g_) >> 2) * HALF + ((g_) & 3) * 16) * 4096 + col0; \
;             _Pragma("unroll") for (int bj = 0; bj < 2; ++bj) q16[slot_][bj] = *(const u32x4*)(base16 + o_ + bj * HALF); } while (0)
;     DI void operator()(f32x4 (&acc)[2][2][4][2], const Unit& u, int wr, int wc, int fr, int fq) const {
;         const int row0 = u.pm * BM + wr * 64 + fr, col0 = u.pn * BM + wc * 32 + 8 * fq;
;         u32x4 q16[2][2];
;     ...
;         EF_LOAD(0, 0); EF_LOAD(1, 1);
; #pragma unroll
;         for (int g = 0; g < 8; ++g) { const int ai = g >> 2, m = g & 3; const int row = row0 + ai * HALF + m * 16;
;             f32x4 cur[2][2];
; #pragma unroll
;             for (int bj = 0; bj < 2; ++bj) { const u32x4 w = q16[g & 1][bj]; cur[bj][0] = (f32x4){bflo(w.x), bfhi(w.x), bflo(w.y), bfhi(w.y)}; cur[bj][1] = (f32x4){bflo(w.z), bfhi(w.z), bflo(w.w), bfhi(w.w)}; }
;             if (g + 2 < 8) EF_LOAD(g & 1, g + 2);
;             const float s = __builtin_amdgcn_rsqf(ssq_epi[row] * (1.0f / 8192.0f) + 1e-6f);
;             float ss = 0.f;
; #pragma unroll
;             for (int bj = 0; bj < 2; ++bj) { const f32x4 v0 = cur[bj][0] + acc[ai][bj][m][0] * s, v1 = cur[bj][1] + acc[ai][bj][m][1] * s;
;                 ss += ((v0[0] * v0[0] + v0[1] * v0[1]) + (v0[2] * v0[2] + v0[3] * v0[3])) + ((v1[0] * v1[0] + v1[1] * v1[1]) + (v1[2] * v1[2] + v1[3] * v1[3]));
;                 acc[ai][bj][m][0] = v0; acc[ai][bj][m][1] = v1; }
;             ss = fq_sum(ss);
;             if (fq == 0) unsafeAtomicAdd(ssq_out + row, ss); }
.LBB0_885:
	v_lshl_add_u32 v164, s62, 8, v167
	v_lshl_or_b32 v168, s34, 8, v191
	v_ashrrev_i32_e32 v165, 31, v164
	v_ashrrev_i32_e32 v169, 31, v168
	v_lshlrev_b64 v[128:129], 13, v[164:165]
	v_lshl_add_u64 v[184:185], s[42:43], 0, v[128:129]
	v_lshlrev_b64 v[128:129], 1, v[168:169]
	v_lshl_add_u64 v[130:131], v[184:185], 0, v[128:129]
	v_lshl_add_u64 v[186:187], v[164:165], 2, s[50:51]
	global_load_dwordx4 v[170:173], v[130:131], off
	global_load_dwordx4 v[174:177], v[130:131], off offset:256
	global_load_dword v199, v[186:187], off
	global_load_dword v240, v[186:187], off offset:64
	global_load_dword v241, v[186:187], off offset:128
	global_load_dword v242, v[186:187], off offset:192
	global_load_dword v243, v[186:187], off offset:512
	global_load_dword v244, v[186:187], off offset:576
	global_load_dword v245, v[186:187], off offset:640
	global_load_dword v246, v[186:187], off offset:704
	v_or_b32_e32 v162, 16, v164
	v_or_b32_e32 v160, 32, v164
	v_ashrrev_i32_e32 v163, 31, v162
	v_ashrrev_i32_e32 v161, 31, v160
	v_lshlrev_b64 v[130:131], 13, v[162:163]
	v_lshlrev_b64 v[132:133], 13, v[160:161]
	v_lshl_add_u64 v[130:131], s[42:43], 0, v[130:131]
	v_lshl_add_u64 v[132:133], s[42:43], 0, v[132:133]
	v_lshl_add_u64 v[130:131], v[130:131], 0, v[128:129]
	v_lshl_add_u64 v[128:129], v[132:133], 0, v[128:129]
	global_load_dwordx4 v[140:143], v[130:131], off
	global_load_dwordx4 v[136:139], v[130:131], off offset:256
	global_load_dwordx4 v[132:135], v[128:129], off
	s_nop 0
	global_load_dwordx4 v[128:131], v[128:129], off offset:256
	s_waitcnt vmcnt(0)
	v_lshlrev_b32_e32 v180, 16, v172
	v_and_b32_e32 v181, 0xffff0000, v172
	v_fmamk_f32 v172, v199, 0x39000000, v195
	v_rsq_f32_e32 v200, v172
	v_lshlrev_b32_e32 v178, 16, v170
	v_and_b32_e32 v179, 0xffff0000, v170
	v_lshlrev_b32_e32 v170, 16, v171
	v_and_b32_e32 v171, 0xffff0000, v171
	v_lshlrev_b32_e32 v182, 16, v173
	v_and_b32_e32 v183, 0xffff0000, v173
	v_lshlrev_b32_e32 v188, 16, v174
	v_and_b32_e32 v189, 0xffff0000, v174
	v_lshlrev_b32_e32 v196, 16, v175
	v_and_b32_e32 v197, 0xffff0000, v175
	v_lshlrev_b32_e32 v198, 16, v176
	v_and_b32_e32 v199, 0xffff0000, v176
	v_lshlrev_b32_e32 v202, 16, v177
	v_and_b32_e32 v203, 0xffff0000, v177
	v_pk_fma_f32 v[126:127], v[126:127], v[200:201], v[170:171] op_sel_hi:[1,0,1]
	v_pk_fma_f32 v[172:173], v[124:125], v[200:201], v[178:179] op_sel_hi:[1,0,1]
	v_pk_fma_f32 v[124:125], v[122:123], v[200:201], v[182:183] op_sel_hi:[1,0,1]
	v_pk_fma_f32 v[174:175], v[120:121], v[200:201], v[180:181] op_sel_hi:[1,0,1]
	v_pk_fma_f32 v[176:177], v[118:119], v[200:201], v[196:197] op_sel_hi:[1,0,1]
	v_pk_fma_f32 v[180:181], v[116:117], v[200:201], v[188:189] op_sel_hi:[1,0,1]
	v_pk_fma_f32 v[170:171], v[114:115], v[200:201], v[202:203] op_sel_hi:[1,0,1]
	v_pk_fma_f32 v[178:179], v[112:113], v[200:201], v[198:199] op_sel_hi:[1,0,1]
	v_mul_f32_e32 v112, v173, v173
	v_mul_f32_e32 v113, v127, v127
	v_mul_f32_e32 v114, v175, v175
	v_mul_f32_e32 v115, v125, v125
	v_mul_f32_e32 v116, v181, v181
	v_mul_f32_e32 v117, v177, v177
	v_mul_f32_e32 v118, v179, v179
	v_mul_f32_e32 v119, v171, v171
	v_fmac_f32_e32 v112, v172, v172
	v_fmac_f32_e32 v113, v126, v126
	v_fmac_f32_e32 v114, v174, v174
	v_fmac_f32_e32 v115, v124, v124
	v_fmac_f32_e32 v116, v180, v180
	v_fmac_f32_e32 v117, v176, v176
	v_fmac_f32_e32 v118, v178, v178
	v_fmac_f32_e32 v119, v170, v170
	v_add_f32_e32 v112, v112, v113
	v_add_f32_e32 v113, v114, v115
	v_add_f32_e32 v114, v116, v117
	v_add_f32_e32 v115, v118, v119
	v_add_f32_e32 v112, v112, v113
	v_add_f32_e32 v113, v114, v115
	v_add_f32_e32 v112, v112, v113
	v_mov_b32_e32 v113, v112
	s_nop 1
	v_permlane16_swap_b32_e32 v112, v113
	v_add_f32_e32 v112, v112, v113
	v_mov_b32_e32 v113, v112
	s_nop 1
	v_permlane32_swap_b32_e32 v112, v113
	v_lshl_add_u64 v[120:121], v[164:165], 2, s[12:13]
	s_and_saveexec_b64 s[6:7], s[0:1]
	s_cbranch_execz .LBB0_887
	v_add_f32_e32 v112, v112, v113
	global_atomic_add_f32 v[120:121], v112, off
.LBB0_887:
	s_or_b64 exec, exec, s[6:7]
	v_lshl_add_u64 v[112:113], v[162:163], 2, s[50:51]
	v_mov_b32_e32 v201, v240
	v_or_b32_e32 v122, 48, v164
	v_ashrrev_i32_e32 v123, 31, v122
	v_lshlrev_b64 v[112:113], 13, v[122:123]
	v_lshl_add_u64 v[112:113], s[42:43], 0, v[112:113]
	v_lshl_add_u64 v[112:113], v[168:169], 1, v[112:113]
	global_load_dwordx4 v[116:119], v[112:113], off
	s_nop 0
	global_load_dwordx4 v[112:115], v[112:113], off offset:256
	v_lshlrev_b32_e32 v196, 16, v136
	v_and_b32_e32 v197, 0xffff0000, v136
	v_lshlrev_b32_e32 v182, 16, v140
	v_and_b32_e32 v183, 0xffff0000, v140
	v_lshlrev_b32_e32 v140, 16, v141
	v_and_b32_e32 v141, 0xffff0000, v141
	v_lshlrev_b32_e32 v188, 16, v142
	v_and_b32_e32 v189, 0xffff0000, v142
	v_lshlrev_b32_e32 v142, 16, v143
	v_and_b32_e32 v143, 0xffff0000, v143
	v_lshlrev_b32_e32 v198, 16, v137
	v_and_b32_e32 v199, 0xffff0000, v137
	v_lshlrev_b32_e32 v200, 16, v138
	s_waitcnt vmcnt(3)
	v_fmamk_f32 v136, v201, 0x39000000, v195
	v_rsq_f32_e32 v202, v136
	v_and_b32_e32 v201, 0xffff0000, v138
	v_lshlrev_b32_e32 v138, 16, v139
	v_and_b32_e32 v139, 0xffff0000, v139
	v_pk_fma_f32 v[110:111], v[110:111], v[202:203], v[140:141] op_sel_hi:[1,0,1]
	v_pk_fma_f32 v[108:109], v[108:109], v[202:203], v[182:183] op_sel_hi:[1,0,1]
	v_pk_fma_f32 v[106:107], v[106:107], v[202:203], v[142:143] op_sel_hi:[1,0,1]
	v_pk_fma_f32 v[136:137], v[104:105], v[202:203], v[188:189] op_sel_hi:[1,0,1]
	v_pk_fma_f32 v[140:141], v[102:103], v[202:203], v[198:199] op_sel_hi:[1,0,1]
	v_pk_fma_f32 v[182:183], v[100:101], v[202:203], v[196:197] op_sel_hi:[1,0,1]
	v_pk_fma_f32 v[138:139], v[98:99], v[202:203], v[138:139] op_sel_hi:[1,0,1]
	v_pk_fma_f32 v[142:143], v[96:97], v[202:203], v[200:201] op_sel_hi:[1,0,1]
	v_mul_f32_e32 v96, v109, v109
	v_mul_f32_e32 v97, v111, v111
	v_mul_f32_e32 v98, v137, v137
	v_mul_f32_e32 v99, v107, v107
	v_mul_f32_e32 v100, v183, v183
	v_mul_f32_e32 v101, v141, v141
	v_mul_f32_e32 v102, v143, v143
	v_mul_f32_e32 v103, v139, v139
	v_fmac_f32_e32 v96, v108, v108
	v_fmac_f32_e32 v97, v110, v110
	v_fmac_f32_e32 v98, v136, v136
	v_fmac_f32_e32 v99, v106, v106
	v_fmac_f32_e32 v100, v182, v182
	v_fmac_f32_e32 v101, v140, v140
	v_fmac_f32_e32 v102, v142, v142
	v_fmac_f32_e32 v103, v138, v138
	v_add_f32_e32 v96, v96, v97
	v_add_f32_e32 v97, v98, v99
	v_add_f32_e32 v98, v100, v101
	v_add_f32_e32 v99, v102, v103
	v_add_f32_e32 v96, v96, v97
	v_add_f32_e32 v97, v98, v99
	v_add_f32_e32 v96, v96, v97
	v_mov_b32_e32 v97, v96
	s_nop 1
	v_permlane16_swap_b32_e32 v96, v97
	v_add_f32_e32 v96, v96, v97
	v_mov_b32_e32 v97, v96
	s_nop 1
	v_permlane32_swap_b32_e32 v96, v97
	s_and_saveexec_b64 s[6:7], s[0:1]
	s_cbranch_execz .LBB0_889
	v_add_f32_e32 v96, v96, v97
	global_atomic_add_f32 v[120:121], v96, off offset:64
; DI float bflo(unsigned w) { return __uint_as_float(w << 16); }
; DI float bfhi(unsigned w) { return __uint_as_float(w & 0xffff0000u); }
; #define EF_LOAD(slot_, g_) do { const size_t o_ = (size_t)(row0 + ((g_) >> 2) * HALF + ((g_) & 3) * 16) * 4096 + col0; \
;             _Pragma("unroll") for (int bj = 0; bj < 2; ++bj) q16[slot_][bj] = *(const u32x4*)(base16 + o_ + bj * HALF); } while (0)
;     DI void operator()(f32x4 (&acc)[2][2][4][2], const Unit& u, int wr, int wc, int fr, int fq) const {
;     ...
;         for (int g = 0; g < 8; ++g) { const int ai = g >> 2, m = g & 3; const int row = row0 + ai * HALF + m * 16;
;             f32x4 cur[2][2];
; #pragma unroll
;             for (int bj = 0; bj < 2; ++bj) { const u32x4 w = q16[g & 1][bj]; cur[bj][0] = (f32x4){bflo(w.x), bfhi(w.x), bflo(w.y), bfhi(w.y)}; cur[bj][1] = (f32x4){bflo(w.z), bfhi(w.z), bflo(w.w), bfhi(w.w)}; }
;             if (g + 2 < 8) EF_LOAD(g & 1, g + 2);
;             const float s = __builtin_amdgcn_rsqf(ssq_epi[row] * (1.0f / 8192.0f) + 1e-6f);
;             float ss = 0.f;
; #pragma unroll
;             for (int bj = 0; bj < 2; ++bj) { const f32x4 v0 = cur[bj][0] + acc[ai][bj][m][0] * s, v1 = cur[bj][1] + acc[ai][bj][m][1] * s;
;                 ss += ((v0[0] * v0[0] + v0[1] * v0[1]) + (v0[2] * v0[2] + v0[3] * v0[3])) + ((v1[0] * v1[0] + v1[1] * v1[1]) + (v1[2] * v1[2] + v1[3] * v1[3]));
;                 acc[ai][bj][m][0] = v0; acc[ai][bj][m][1] = v1; }
;             ss = fq_sum(ss);
;             if (fq == 0) unsafeAtomicAdd(ssq_out + row, ss); }
.LBB0_889:
	s_or_b64 exec, exec, s[6:7]
	v_lshl_add_u64 v[96:97], v[160:161], 2, s[50:51]
	v_mov_b32_e32 v201, v241
	v_add_u32_e32 v104, 0x80, v164
	v_ashrrev_i32_e32 v105, 31, v104
	v_lshlrev_b64 v[96:97], 13, v[104:105]
	v_lshl_add_u64 v[96:97], s[42:43], 0, v[96:97]
	v_lshl_add_u64 v[96:97], v[168:169], 1, v[96:97]
	global_load_dwordx4 v[100:103], v[96:97], off
	s_nop 0
	global_load_dwordx4 v[96:99], v[96:97], off offset:256
	v_lshlrev_b32_e32 v188, 16, v132
	v_and_b32_e32 v189, 0xffff0000, v132
	v_lshlrev_b32_e32 v132, 16, v133
	v_and_b32_e32 v133, 0xffff0000, v133
	v_lshlrev_b32_e32 v196, 16, v134
	v_and_b32_e32 v197, 0xffff0000, v134
	v_lshlrev_b32_e32 v134, 16, v135
	v_and_b32_e32 v135, 0xffff0000, v135
	v_lshlrev_b32_e32 v198, 16, v128
	v_and_b32_e32 v199, 0xffff0000, v128
	v_lshlrev_b32_e32 v128, 16, v129
	v_and_b32_e32 v129, 0xffff0000, v129
	v_lshlrev_b32_e32 v200, 16, v130
	v_lshlrev_b32_e32 v204, 16, v131
	v_and_b32_e32 v205, 0xffff0000, v131
	s_waitcnt vmcnt(3)
	v_fmamk_f32 v201, v201, 0x39000000, v195
	v_rsq_f32_e32 v202, v201
	v_and_b32_e32 v201, 0xffff0000, v130
	v_pk_fma_f32 v[94:95], v[94:95], v[202:203], v[132:133] op_sel_hi:[1,0,1]
	v_pk_fma_f32 v[92:93], v[92:93], v[202:203], v[188:189] op_sel_hi:[1,0,1]
	v_pk_fma_f32 v[90:91], v[90:91], v[202:203], v[134:135] op_sel_hi:[1,0,1]
	v_pk_fma_f32 v[88:89], v[88:89], v[202:203], v[196:197] op_sel_hi:[1,0,1]
	v_pk_fma_f32 v[130:131], v[86:87], v[202:203], v[128:129] op_sel_hi:[1,0,1]
	v_pk_fma_f32 v[134:135], v[84:85], v[202:203], v[198:199] op_sel_hi:[1,0,1]
	v_pk_fma_f32 v[128:129], v[82:83], v[202:203], v[204:205] op_sel_hi:[1,0,1]
	v_pk_fma_f32 v[132:133], v[80:81], v[202:203], v[200:201] op_sel_hi:[1,0,1]
	v_mul_f32_e32 v80, v93, v93
	v_mul_f32_e32 v81, v95, v95
	v_mul_f32_e32 v82, v89, v89
	v_mul_f32_e32 v83, v91, v91
	v_mul_f32_e32 v84, v135, v135
	v_mul_f32_e32 v85, v131, v131
	v_mul_f32_e32 v86, v133, v133
	v_mul_f32_e32 v87, v129, v129
	v_fmac_f32_e32 v80, v92, v92
	v_fmac_f32_e32 v81, v94, v94
	v_fmac_f32_e32 v82, v88, v88
	v_fmac_f32_e32 v83, v90, v90
	v_fmac_f32_e32 v84, v134, v134
	v_fmac_f32_e32 v85, v130, v130
	v_fmac_f32_e32 v86, v132, v132
	v_fmac_f32_e32 v87, v128, v128
	v_add_f32_e32 v80, v80, v81
	v_add_f32_e32 v81, v82, v83
	v_add_f32_e32 v82, v84, v85
	v_add_f32_e32 v83, v86, v87
	v_add_f32_e32 v80, v80, v81
	v_add_f32_e32 v81, v82, v83
	v_add_f32_e32 v80, v80, v81
	v_mov_b32_e32 v81, v80
	s_nop 1
	v_permlane16_swap_b32_e32 v80, v81
	v_add_f32_e32 v80, v80, v81
	v_mov_b32_e32 v81, v80
	s_nop 1
	v_permlane32_swap_b32_e32 v80, v81
	s_and_saveexec_b64 s[6:7], s[0:1]
	s_cbranch_execz .LBB0_891
	v_add_f32_e32 v80, v80, v81
	global_atomic_add_f32 v[120:121], v80, off offset:128
.LBB0_891:
	s_or_b64 exec, exec, s[6:7]
	v_lshl_add_u64 v[80:81], v[122:123], 2, s[50:51]
	v_mov_b32_e32 v201, v242
	v_lshl_add_u64 v[80:81], v[168:169], 1, v[184:185]
	v_lshl_add_u64 v[82:83], v[80:81], 0, s[24:25]
	v_add_co_u32_e32 v80, vcc, s60, v80
	v_lshlrev_b32_e32 v196, 16, v112
	s_nop 0
	v_addc_co_u32_e32 v81, vcc, 0, v81, vcc
	global_load_dwordx4 v[84:87], v[80:81], off
	s_nop 0
	global_load_dwordx4 v[80:83], v[82:83], off offset:256
	v_and_b32_e32 v197, 0xffff0000, v112
	v_lshlrev_b32_e32 v184, 16, v116
	v_and_b32_e32 v185, 0xffff0000, v116
	v_lshlrev_b32_e32 v116, 16, v117
	v_and_b32_e32 v117, 0xffff0000, v117
	v_lshlrev_b32_e32 v188, 16, v118
	v_and_b32_e32 v189, 0xffff0000, v118
	v_lshlrev_b32_e32 v118, 16, v119
	v_and_b32_e32 v119, 0xffff0000, v119
	v_lshlrev_b32_e32 v198, 16, v113
	v_and_b32_e32 v199, 0xffff0000, v113
	v_lshlrev_b32_e32 v200, 16, v114
	s_waitcnt vmcnt(3)
	v_fmamk_f32 v112, v201, 0x39000000, v195
	v_rsq_f32_e32 v202, v112
	v_and_b32_e32 v201, 0xffff0000, v114
	v_lshlrev_b32_e32 v114, 16, v115
	v_and_b32_e32 v115, 0xffff0000, v115
	v_pk_fma_f32 v[78:79], v[78:79], v[202:203], v[116:117] op_sel_hi:[1,0,1]
	v_pk_fma_f32 v[76:77], v[76:77], v[202:203], v[184:185] op_sel_hi:[1,0,1]
	v_pk_fma_f32 v[74:75], v[74:75], v[202:203], v[118:119] op_sel_hi:[1,0,1]
	v_pk_fma_f32 v[112:113], v[72:73], v[202:203], v[188:189] op_sel_hi:[1,0,1]
	v_pk_fma_f32 v[116:117], v[70:71], v[202:203], v[198:199] op_sel_hi:[1,0,1]
	v_pk_fma_f32 v[184:185], v[68:69], v[202:203], v[196:197] op_sel_hi:[1,0,1]
	v_pk_fma_f32 v[114:115], v[66:67], v[202:203], v[114:115] op_sel_hi:[1,0,1]
	v_pk_fma_f32 v[118:119], v[64:65], v[202:203], v[200:201] op_sel_hi:[1,0,1]
	v_mul_f32_e32 v64, v77, v77
	v_mul_f32_e32 v65, v79, v79
	v_mul_f32_e32 v66, v113, v113
	v_mul_f32_e32 v67, v75, v75
	v_mul_f32_e32 v68, v185, v185
	v_mul_f32_e32 v69, v117, v117
	v_mul_f32_e32 v70, v119, v119
	v_mul_f32_e32 v71, v115, v115
	v_fmac_f32_e32 v64, v76, v76
	v_fmac_f32_e32 v65, v78, v78
	v_fmac_f32_e32 v66, v112, v112
	v_fmac_f32_e32 v67, v74, v74
	v_fmac_f32_e32 v68, v184, v184
	v_fmac_f32_e32 v69, v116, v116
	v_fmac_f32_e32 v70, v118, v118
	v_fmac_f32_e32 v71, v114, v114
	v_add_f32_e32 v64, v64, v65
	v_add_f32_e32 v65, v66, v67
	v_add_f32_e32 v66, v68, v69
	v_add_f32_e32 v67, v70, v71
	v_add_f32_e32 v64, v64, v65
	v_add_f32_e32 v65, v66, v67
	v_add_f32_e32 v64, v64, v65
	v_mov_b32_e32 v65, v64
	s_nop 1
	v_permlane16_swap_b32_e32 v64, v65
	v_add_f32_e32 v64, v64, v65
	v_mov_b32_e32 v65, v64
	s_nop 1
	v_permlane32_swap_b32_e32 v64, v65
	s_and_saveexec_b64 s[6:7], s[0:1]
	s_cbranch_execz .LBB0_893
	v_add_f32_e32 v64, v64, v65
	global_atomic_add_f32 v[120:121], v64, off offset:192
; DI float bflo(unsigned w) { return __uint_as_float(w << 16); }
; DI float bfhi(unsigned w) { return __uint_as_float(w & 0xffff0000u); }
; #define EF_LOAD(slot_, g_) do { const size_t o_ = (size_t)(row0 + ((g_) >> 2) * HALF + ((g_) & 3) * 16) * 4096 + col0; \
;             _Pragma("unroll") for (int bj = 0; bj < 2; ++bj) q16[slot_][bj] = *(const u32x4*)(base16 + o_ + bj * HALF); } while (0)
;     DI void operator()(f32x4 (&acc)[2][2][4][2], const Unit& u, int wr, int wc, int fr, int fq) const {
;     ...
;         for (int g = 0; g < 8; ++g) { const int ai = g >> 2, m = g & 3; const int row = row0 + ai * HALF + m * 16;
;             f32x4 cur[2][2];
; #pragma unroll
;             for (int bj = 0; bj < 2; ++bj) { const u32x4 w = q16[g & 1][bj]; cur[bj][0] = (f32x4){bflo(w.x), bfhi(w.x), bflo(w.y), bfhi(w.y)}; cur[bj][1] = (f32x4){bflo(w.z), bfhi(w.z), bflo(w.w), bfhi(w.w)}; }
;             if (g + 2 < 8) EF_LOAD(g & 1, g + 2);
;             const float s = __builtin_amdgcn_rsqf(ssq_epi[row] * (1.0f / 8192.0f) + 1e-6f);
;             float ss = 0.f;
; #pragma unroll
;             for (int bj = 0; bj < 2; ++bj) { const f32x4 v0 = cur[bj][0] + acc[ai][bj][m][0] * s, v1 = cur[bj][1] + acc[ai][bj][m][1] * s;
;                 ss += ((v0[0] * v0[0] + v0[1] * v0[1]) + (v0[2] * v0[2] + v0[3] * v0[3])) + ((v1[0] * v1[0] + v1[1] * v1[1]) + (v1[2] * v1[2] + v1[3] * v1[3]));
;                 acc[ai][bj][m][0] = v0; acc[ai][bj][m][1] = v1; }
;             ss = fq_sum(ss);
;             if (fq == 0) unsafeAtomicAdd(ssq_out + row, ss); }
.LBB0_893:
	s_or_b64 exec, exec, s[6:7]
	v_mov_b32_e32 v201, v243
	v_or_b32_e32 v72, 32, v104
	v_ashrrev_i32_e32 v73, 31, v72
	v_lshlrev_b64 v[64:65], 13, v[72:73]
	v_lshl_add_u64 v[64:65], s[42:43], 0, v[64:65]
	v_lshl_add_u64 v[64:65], v[168:169], 1, v[64:65]
	global_load_dwordx4 v[68:71], v[64:65], off
	s_nop 0
	global_load_dwordx4 v[64:67], v[64:65], off offset:256
	v_lshlrev_b32_e32 v196, 16, v96
	v_and_b32_e32 v197, 0xffff0000, v96
	v_lshlrev_b32_e32 v186, 16, v100
	v_and_b32_e32 v187, 0xffff0000, v100
	v_lshlrev_b32_e32 v100, 16, v101
	v_and_b32_e32 v101, 0xffff0000, v101
	v_lshlrev_b32_e32 v188, 16, v102
	v_and_b32_e32 v189, 0xffff0000, v102
	v_lshlrev_b32_e32 v102, 16, v103
	v_and_b32_e32 v103, 0xffff0000, v103
	v_lshlrev_b32_e32 v198, 16, v97
	v_and_b32_e32 v199, 0xffff0000, v97
	v_lshlrev_b32_e32 v200, 16, v98
	s_waitcnt vmcnt(3)
	v_fmamk_f32 v96, v201, 0x39000000, v195
	v_rsq_f32_e32 v202, v96
	v_and_b32_e32 v201, 0xffff0000, v98
	v_lshlrev_b32_e32 v98, 16, v99
	v_and_b32_e32 v99, 0xffff0000, v99
	v_pk_fma_f32 v[62:63], v[62:63], v[202:203], v[100:101] op_sel_hi:[1,0,1]
	v_pk_fma_f32 v[60:61], v[60:61], v[202:203], v[186:187] op_sel_hi:[1,0,1]
	v_pk_fma_f32 v[58:59], v[58:59], v[202:203], v[102:103] op_sel_hi:[1,0,1]
	v_pk_fma_f32 v[96:97], v[56:57], v[202:203], v[188:189] op_sel_hi:[1,0,1]
	v_pk_fma_f32 v[100:101], v[54:55], v[202:203], v[198:199] op_sel_hi:[1,0,1]
	v_pk_fma_f32 v[186:187], v[52:53], v[202:203], v[196:197] op_sel_hi:[1,0,1]
	v_pk_fma_f32 v[98:99], v[50:51], v[202:203], v[98:99] op_sel_hi:[1,0,1]
	v_pk_fma_f32 v[102:103], v[48:49], v[202:203], v[200:201] op_sel_hi:[1,0,1]
	v_mul_f32_e32 v48, v61, v61
	v_mul_f32_e32 v49, v63, v63
	v_mul_f32_e32 v50, v97, v97
	v_mul_f32_e32 v51, v59, v59
	v_mul_f32_e32 v52, v187, v187
	v_mul_f32_e32 v53, v101, v101
	v_mul_f32_e32 v54, v103, v103
	v_mul_f32_e32 v55, v99, v99
	v_fmac_f32_e32 v48, v60, v60
	v_fmac_f32_e32 v49, v62, v62
	v_fmac_f32_e32 v50, v96, v96
	v_fmac_f32_e32 v51, v58, v58
	v_fmac_f32_e32 v52, v186, v186
	v_fmac_f32_e32 v53, v100, v100
	v_fmac_f32_e32 v54, v102, v102
	v_fmac_f32_e32 v55, v98, v98
	v_add_f32_e32 v48, v48, v49
	v_add_f32_e32 v49, v50, v51
	v_add_f32_e32 v50, v52, v53
	v_add_f32_e32 v51, v54, v55
	v_add_f32_e32 v48, v48, v49
	v_add_f32_e32 v49, v50, v51
	v_add_f32_e32 v48, v48, v49
	v_mov_b32_e32 v49, v48
	s_nop 1
	v_permlane16_swap_b32_e32 v48, v49
	v_add_f32_e32 v48, v48, v49
	v_mov_b32_e32 v49, v48
	s_nop 1
	v_permlane32_swap_b32_e32 v48, v49
	s_and_saveexec_b64 s[6:7], s[0:1]
	s_cbranch_execz .LBB0_895
	v_add_f32_e32 v48, v48, v49
	global_atomic_add_f32 v[120:121], v48, off offset:512
.LBB0_895:
	s_or_b64 exec, exec, s[6:7]
	v_or_b32_e32 v188, 16, v104
	v_ashrrev_i32_e32 v189, 31, v188
	v_lshl_add_u64 v[48:49], v[188:189], 2, s[50:51]
	v_mov_b32_e32 v203, v244
	v_or_b32_e32 v56, 48, v104
	v_ashrrev_i32_e32 v57, 31, v56
	v_lshlrev_b64 v[48:49], 13, v[56:57]
	v_lshl_add_u64 v[48:49], s[42:43], 0, v[48:49]
	v_lshl_add_u64 v[48:49], v[168:169], 1, v[48:49]
	global_load_dwordx4 v[52:55], v[48:49], off
	s_nop 0
	global_load_dwordx4 v[48:51], v[48:49], off offset:256
	v_lshlrev_b32_e32 v196, 16, v84
	v_and_b32_e32 v197, 0xffff0000, v84
	v_lshlrev_b32_e32 v84, 16, v85
	v_and_b32_e32 v85, 0xffff0000, v85
	v_lshlrev_b32_e32 v198, 16, v86
	v_and_b32_e32 v199, 0xffff0000, v86
	v_lshlrev_b32_e32 v86, 16, v87
	v_and_b32_e32 v87, 0xffff0000, v87
	v_lshlrev_b32_e32 v200, 16, v80
	v_and_b32_e32 v201, 0xffff0000, v80
	v_lshlrev_b32_e32 v80, 16, v81
	v_and_b32_e32 v81, 0xffff0000, v81
	v_lshlrev_b32_e32 v202, 16, v82
	s_waitcnt vmcnt(3)
	v_fmamk_f32 v203, v203, 0x39000000, v195
	v_rsq_f32_e32 v204, v203
	v_and_b32_e32 v203, 0xffff0000, v82
	v_lshlrev_b32_e32 v82, 16, v83
	v_and_b32_e32 v83, 0xffff0000, v83
	v_pk_fma_f32 v[46:47], v[46:47], v[204:205], v[84:85] op_sel_hi:[1,0,1]
	v_pk_fma_f32 v[44:45], v[44:45], v[204:205], v[196:197] op_sel_hi:[1,0,1]
	v_pk_fma_f32 v[42:43], v[42:43], v[204:205], v[86:87] op_sel_hi:[1,0,1]
	v_pk_fma_f32 v[40:41], v[40:41], v[204:205], v[198:199] op_sel_hi:[1,0,1]
	v_pk_fma_f32 v[38:39], v[38:39], v[204:205], v[80:81] op_sel_hi:[1,0,1]
	v_pk_fma_f32 v[36:37], v[36:37], v[204:205], v[200:201] op_sel_hi:[1,0,1]
	v_pk_fma_f32 v[34:35], v[34:35], v[204:205], v[82:83] op_sel_hi:[1,0,1]
	v_pk_fma_f32 v[32:33], v[32:33], v[204:205], v[202:203] op_sel_hi:[1,0,1]
	v_mul_f32_e32 v80, v45, v45
	v_mul_f32_e32 v81, v47, v47
	v_mul_f32_e32 v82, v41, v41
	v_mul_f32_e32 v83, v43, v43
	v_mul_f32_e32 v84, v37, v37
	v_mul_f32_e32 v85, v39, v39
	v_mul_f32_e32 v86, v33, v33
	v_mul_f32_e32 v87, v35, v35
	v_fmac_f32_e32 v80, v44, v44
	v_fmac_f32_e32 v81, v46, v46
	v_fmac_f32_e32 v82, v40, v40
	v_fmac_f32_e32 v83, v42, v42
	v_fmac_f32_e32 v84, v36, v36
	v_fmac_f32_e32 v85, v38, v38
	v_fmac_f32_e32 v86, v32, v32
	v_fmac_f32_e32 v87, v34, v34
	v_add_f32_e32 v80, v80, v81
	v_add_f32_e32 v81, v82, v83
	v_add_f32_e32 v82, v84, v85
	v_add_f32_e32 v83, v86, v87
	v_add_f32_e32 v80, v80, v81
	v_add_f32_e32 v81, v82, v83
	v_add_f32_e32 v80, v80, v81
	v_mov_b32_e32 v81, v80
	s_nop 1
	v_permlane16_swap_b32_e32 v80, v81
	v_add_f32_e32 v80, v80, v81
	v_mov_b32_e32 v81, v80
	s_nop 1
	v_permlane32_swap_b32_e32 v80, v81
	s_and_saveexec_b64 s[6:7], s[0:1]
	s_cbranch_execz .LBB0_897
	v_add_f32_e32 v80, v80, v81
	global_atomic_add_f32 v[120:121], v80, off offset:576
; DI float bflo(unsigned w) { return __uint_as_float(w << 16); }
; DI float bfhi(unsigned w) { return __uint_as_float(w & 0xffff0000u); }
; #define EF_LOAD(slot_, g_) do { const size_t o_ = (size_t)(row0 + ((g_) >> 2) * HALF + ((g_) & 3) * 16) * 4096 + col0; \
;             _Pragma("unroll") for (int bj = 0; bj < 2; ++bj) q16[slot_][bj] = *(const u32x4*)(base16 + o_ + bj * HALF); } while (0)
;     DI void operator()(f32x4 (&acc)[2][2][4][2], const Unit& u, int wr, int wc, int fr, int fq) const {
;     ...
;         for (int g = 0; g < 8; ++g) { const int ai = g >> 2, m = g & 3; const int row = row0 + ai * HALF + m * 16;
;             f32x4 cur[2][2];
; #pragma unroll
;             for (int bj = 0; bj < 2; ++bj) { const u32x4 w = q16[g & 1][bj]; cur[bj][0] = (f32x4){bflo(w.x), bfhi(w.x), bflo(w.y), bfhi(w.y)}; cur[bj][1] = (f32x4){bflo(w.z), bfhi(w.z), bflo(w.w), bfhi(w.w)}; }
;             if (g + 2 < 8) EF_LOAD(g & 1, g + 2);
;             const float s = __builtin_amdgcn_rsqf(ssq_epi[row] * (1.0f / 8192.0f) + 1e-6f);
;             float ss = 0.f;
; #pragma unroll
;             for (int bj = 0; bj < 2; ++bj) { const f32x4 v0 = cur[bj][0] + acc[ai][bj][m][0] * s, v1 = cur[bj][1] + acc[ai][bj][m][1] * s;
;                 ss += ((v0[0] * v0[0] + v0[1] * v0[1]) + (v0[2] * v0[2] + v0[3] * v0[3])) + ((v1[0] * v1[0] + v1[1] * v1[1]) + (v1[2] * v1[2] + v1[3] * v1[3]));
;                 acc[ai][bj][m][0] = v0; acc[ai][bj][m][1] = v1; }
;             ss = fq_sum(ss);
;             if (fq == 0) unsafeAtomicAdd(ssq_out + row, ss); }
.LBB0_897:
	s_or_b64 exec, exec, s[6:7]
	v_lshl_add_u64 v[80:81], v[72:73], 2, s[50:51]
	v_mov_b32_e32 v87, v245
	v_lshlrev_b32_e32 v80, 16, v68
	v_and_b32_e32 v81, 0xffff0000, v68
	v_lshlrev_b32_e32 v68, 16, v69
	v_and_b32_e32 v69, 0xffff0000, v69
	v_lshlrev_b32_e32 v82, 16, v70
	v_and_b32_e32 v83, 0xffff0000, v70
	v_lshlrev_b32_e32 v70, 16, v71
	v_and_b32_e32 v71, 0xffff0000, v71
	v_lshlrev_b32_e32 v84, 16, v64
	v_and_b32_e32 v85, 0xffff0000, v64
	v_lshlrev_b32_e32 v64, 16, v65
	v_and_b32_e32 v65, 0xffff0000, v65
	v_lshlrev_b32_e32 v86, 16, v66
	s_waitcnt vmcnt(1)
	v_fmamk_f32 v87, v87, 0x39000000, v195
	v_rsq_f32_e32 v196, v87
	v_and_b32_e32 v87, 0xffff0000, v66
	v_lshlrev_b32_e32 v66, 16, v67
	v_and_b32_e32 v67, 0xffff0000, v67
	v_pk_fma_f32 v[30:31], v[30:31], v[196:197], v[68:69] op_sel_hi:[1,0,1]
	v_pk_fma_f32 v[28:29], v[28:29], v[196:197], v[80:81] op_sel_hi:[1,0,1]
	v_pk_fma_f32 v[26:27], v[26:27], v[196:197], v[70:71] op_sel_hi:[1,0,1]
	v_pk_fma_f32 v[24:25], v[24:25], v[196:197], v[82:83] op_sel_hi:[1,0,1]
	v_pk_fma_f32 v[22:23], v[22:23], v[196:197], v[64:65] op_sel_hi:[1,0,1]
	v_pk_fma_f32 v[20:21], v[20:21], v[196:197], v[84:85] op_sel_hi:[1,0,1]
	v_pk_fma_f32 v[18:19], v[18:19], v[196:197], v[66:67] op_sel_hi:[1,0,1]
	v_pk_fma_f32 v[16:17], v[16:17], v[196:197], v[86:87] op_sel_hi:[1,0,1]
	v_mul_f32_e32 v64, v29, v29
	v_mul_f32_e32 v65, v31, v31
	v_mul_f32_e32 v66, v25, v25
	v_mul_f32_e32 v67, v27, v27
	v_mul_f32_e32 v68, v21, v21
	v_mul_f32_e32 v69, v23, v23
	v_mul_f32_e32 v70, v17, v17
	v_mul_f32_e32 v71, v19, v19
	v_fmac_f32_e32 v64, v28, v28
	v_fmac_f32_e32 v65, v30, v30
	v_fmac_f32_e32 v66, v24, v24
	v_fmac_f32_e32 v67, v26, v26
	v_fmac_f32_e32 v68, v20, v20
	v_fmac_f32_e32 v69, v22, v22
	v_fmac_f32_e32 v70, v16, v16
	v_fmac_f32_e32 v71, v18, v18
	v_add_f32_e32 v64, v64, v65
	v_add_f32_e32 v65, v66, v67
	v_add_f32_e32 v66, v68, v69
	v_add_f32_e32 v67, v70, v71
	v_add_f32_e32 v64, v64, v65
	v_add_f32_e32 v65, v66, v67
	v_add_f32_e32 v64, v64, v65
	v_mov_b32_e32 v65, v64
	s_nop 1
	v_permlane16_swap_b32_e32 v64, v65
	v_add_f32_e32 v64, v64, v65
	v_mov_b32_e32 v65, v64
	s_nop 1
	v_permlane32_swap_b32_e32 v64, v65
	s_and_saveexec_b64 s[6:7], s[0:1]
	s_cbranch_execz .LBB0_899
	v_add_f32_e32 v64, v64, v65
	global_atomic_add_f32 v[120:121], v64, off offset:640
.LBB0_899:
	s_or_b64 exec, exec, s[6:7]
	v_lshl_add_u64 v[64:65], v[56:57], 2, s[50:51]
	v_mov_b32_e32 v81, v246
	v_lshlrev_b32_e32 v68, 16, v48
	v_and_b32_e32 v69, 0xffff0000, v48
	v_lshlrev_b32_e32 v64, 16, v52
	v_and_b32_e32 v65, 0xffff0000, v52
	v_lshlrev_b32_e32 v52, 16, v53
	v_and_b32_e32 v53, 0xffff0000, v53
	v_lshlrev_b32_e32 v66, 16, v54
	v_and_b32_e32 v67, 0xffff0000, v54
	v_lshlrev_b32_e32 v54, 16, v55
	v_and_b32_e32 v55, 0xffff0000, v55
	v_lshlrev_b32_e32 v70, 16, v49
	v_and_b32_e32 v71, 0xffff0000, v49
	v_lshlrev_b32_e32 v80, 16, v50
	v_lshlrev_b32_e32 v84, 16, v51
	v_and_b32_e32 v85, 0xffff0000, v51
	s_waitcnt vmcnt(1)
	v_fmamk_f32 v48, v81, 0x39000000, v195
	v_rsq_f32_e32 v82, v48
	v_and_b32_e32 v81, 0xffff0000, v50
	v_pk_fma_f32 v[48:49], v[14:15], v[82:83], v[52:53] op_sel_hi:[1,0,1]
	v_pk_fma_f32 v[50:51], v[12:13], v[82:83], v[64:65] op_sel_hi:[1,0,1]
	v_pk_fma_f32 v[52:53], v[10:11], v[82:83], v[54:55] op_sel_hi:[1,0,1]
	v_pk_fma_f32 v[54:55], v[8:9], v[82:83], v[66:67] op_sel_hi:[1,0,1]
	v_pk_fma_f32 v[64:65], v[6:7], v[82:83], v[70:71] op_sel_hi:[1,0,1]
	v_pk_fma_f32 v[66:67], v[4:5], v[82:83], v[68:69] op_sel_hi:[1,0,1]
	v_pk_fma_f32 v[68:69], v[2:3], v[82:83], v[84:85] op_sel_hi:[1,0,1]
	v_pk_fma_f32 v[70:71], v[0:1], v[82:83], v[80:81] op_sel_hi:[1,0,1]
	v_mul_f32_e32 v0, v51, v51
	v_mul_f32_e32 v1, v49, v49
	v_mul_f32_e32 v2, v55, v55
	v_mul_f32_e32 v3, v53, v53
	v_mul_f32_e32 v4, v67, v67
	v_mul_f32_e32 v5, v65, v65
	v_mul_f32_e32 v6, v71, v71
	v_mul_f32_e32 v7, v69, v69
	v_fmac_f32_e32 v0, v50, v50
	v_fmac_f32_e32 v1, v48, v48
	v_fmac_f32_e32 v2, v54, v54
	v_fmac_f32_e32 v3, v52, v52
	v_fmac_f32_e32 v4, v66, v66
	v_fmac_f32_e32 v5, v64, v64
	v_fmac_f32_e32 v6, v70, v70
	v_fmac_f32_e32 v7, v68, v68
	v_add_f32_e32 v0, v0, v1
	v_add_f32_e32 v1, v2, v3
	v_add_f32_e32 v2, v4, v5
	v_add_f32_e32 v3, v6, v7
	v_add_f32_e32 v0, v0, v1
	v_add_f32_e32 v1, v2, v3
	v_add_f32_e32 v0, v0, v1
	v_mov_b32_e32 v1, v0
	s_nop 1
	v_permlane16_swap_b32_e32 v0, v1
	v_add_f32_e32 v0, v0, v1
	v_mov_b32_e32 v1, v0
	s_nop 1
	v_permlane32_swap_b32_e32 v0, v1
	s_and_saveexec_b64 s[6:7], s[0:1]
	s_cbranch_execz .LBB0_901
	v_add_f32_e32 v0, v0, v1
	global_atomic_add_f32 v[120:121], v0, off offset:704
